# fused epilogue part 1: half of the residual tile prefetched through LDS-DMA (16 KB per wave in the idle stage buffers), other half keeps the 2-deep register pipeline
# baseline (speedup 1.0000x reference)
;     __device__ __forceinline__ void fused(f32x4 (&acc)[2][2][4][2], const Unit& u, int wr, int wc, int fr, int fq, LAS unsigned char* lds, int wid, int lane) const {
;     ...
;         const int col0 = u.pn * BM + wc * 32 + 4 * fq; const size_t mb = (size_t)(u.pm >> 4) * (NMOD * D);
;         row_exchange(acc, u, wr, wc, fr, fq, lds, wid, lane, slots, cnt);
;         {
;             f32x4 cw[2][2];
; #pragma unroll
;             for (int bj = 0; bj < 2; ++bj)
; #pragma unroll
;                 for (int n = 0; n < 2; ++n) cw[bj][n] = *(const f32x4*)(gate + mb + col0 + bj * HALF + n * 16) * *(const f32x4*)(gpost + col0 + bj * HALF + n * 16);
; #pragma unroll
;             for (int ai = 0; ai < 2; ++ai)
; #pragma unroll
;                 for (int m = 0; m < 4; ++m) { const int r = ai * HALF + wr * 64 + m * 16 + fr; const float r1 = rsqrtf(S[r] * (1.0f / D) + EPS) * wgt; const size_t off = (size_t)(u.pm * BM + r) * D + col0;
; #pragma unroll
;                     for (int bj = 0; bj < 2; ++bj)
; #pragma unroll
;                         for (int n = 0; n < 2; ++n) { const f32x4 xv = *(const f32x4*)(xin + off + bj * HALF + n * 16); const f32x4 xn = xv + (cw[bj][n] * r1) * acc[ai][bj][m][n];
.LBB0_1116:
	s_or_b64 exec, exec, s[48:49]
	v_readlane_b32 s18, v253, 36
	s_lshl_b32 s0, s15, 5
	s_lshl_b32 s1, s86, 8
	s_mul_i32 s15, s18, 45
	s_or_b32 s0, s1, s0
	v_lshrrev_b32_e32 v128, 2, v138
	s_add_i32 s15, s12, s15
	v_and_or_b32 v154, v128, 12, s0
	s_ashr_i32 s0, s33, 4
	s_lshl_b32 s15, s15, 12
	s_mul_hi_i32 s1, s0, 0x2400
	s_mulk_i32 s0, 0x2400
	s_add_u32 s15, s94, s15
	s_addc_u32 s18, s95, 0
	s_lshl_b64 s[94:95], s[0:1], 2
	s_add_u32 s0, s15, s94
	v_ashrrev_i32_e32 v155, 31, v154
	s_addc_u32 s1, s18, s95
	v_lshlrev_b64 v[128:129], 2, v[154:155]
	v_lshl_add_u64 v[132:133], s[0:1], 0, v[128:129]
	s_mov_b64 s[0:1], 0xa300000
	v_lshl_add_u64 v[162:163], v[132:133], 0, s[0:1]
	v_readlane_b32 s0, v253, 43
	v_readlane_b32 s1, v253, 44
	v_lshl_add_u32 v208, v156, 2, 0
	v_lshl_add_u64 v[164:165], s[0:1], 0, v[128:129]
	s_mov_b32 s0, 0xa300000
	v_readlane_b32 s19, v253, 37
	v_add_u32_e32 v158, s50, v156
	v_ashrrev_i32_e32 v159, 31, v158
	v_lshlrev_b64 v[246:247], 10, v[158:159]
	v_lshl_add_u64 v[246:247], v[246:247], 0, v[154:155]
	v_lshlrev_b64 v[246:247], 2, v[246:247]
	v_lshl_add_u64 v[246:247], s[90:91], 0, v[246:247]
	global_load_dwordx4 v[212:215], v[246:247], off
	global_load_dwordx4 v[216:219], v[246:247], off offset:64
	global_load_dwordx4 v[220:223], v[246:247], off offset:512
	global_load_dwordx4 v[224:227], v[246:247], off offset:576
	v_add_u32_e32 v156, 16, v158
	v_ashrrev_i32_e32 v157, 31, v156
	v_lshlrev_b64 v[246:247], 10, v[156:157]
	v_lshl_add_u64 v[246:247], v[246:247], 0, v[154:155]
	v_lshlrev_b64 v[246:247], 2, v[246:247]
	v_lshl_add_u64 v[246:247], s[90:91], 0, v[246:247]
	global_load_dwordx4 v[228:231], v[246:247], off
	global_load_dwordx4 v[232:235], v[246:247], off offset:64
	global_load_dwordx4 v[236:239], v[246:247], off offset:512
	global_load_dwordx4 v[240:243], v[246:247], off offset:576
	v_readfirstlane_b32 s100, v147
	s_mov_b64 s[98:99], 0x1c0
	s_nop 1
	s_lshr_b32 s100, s100, 6
	s_lshl_b32 s100, s100, 14
	s_add_i32 s100, s100, 0x2000
	v_add_u32_e32 v244, 0x80, v158
	v_ashrrev_i32_e32 v245, 31, v244
	v_lshlrev_b64 v[244:245], 10, v[244:245]
	v_lshl_add_u64 v[244:245], v[244:245], 0, v[154:155]
	v_lshlrev_b64 v[244:245], 2, v[244:245]
	v_lshl_add_u64 v[244:245], s[90:91], 0, v[244:245]
	s_add_i32 m0, s100, 0x0
	s_nop 0
	global_load_lds_dwordx4 v[244:245], off
	v_lshl_add_u64 v[244:245], v[244:245], 0, 64
	s_add_i32 m0, s100, 0x400
	s_nop 0
	global_load_lds_dwordx4 v[244:245], off
	v_lshl_add_u64 v[244:245], v[244:245], 0, s[98:99]
	s_add_i32 m0, s100, 0x800
	s_nop 0
	global_load_lds_dwordx4 v[244:245], off
	v_lshl_add_u64 v[244:245], v[244:245], 0, 64
	s_add_i32 m0, s100, 0xc00
	s_nop 0
	global_load_lds_dwordx4 v[244:245], off
	v_add_u32_e32 v244, 0x90, v158
	v_ashrrev_i32_e32 v245, 31, v244
	v_lshlrev_b64 v[244:245], 10, v[244:245]
	v_lshl_add_u64 v[244:245], v[244:245], 0, v[154:155]
	v_lshlrev_b64 v[244:245], 2, v[244:245]
	v_lshl_add_u64 v[244:245], s[90:91], 0, v[244:245]
	s_add_i32 m0, s100, 0x1000
	s_nop 0
	global_load_lds_dwordx4 v[244:245], off
	v_lshl_add_u64 v[244:245], v[244:245], 0, 64
	s_add_i32 m0, s100, 0x1400
	s_nop 0
	global_load_lds_dwordx4 v[244:245], off
	v_lshl_add_u64 v[244:245], v[244:245], 0, s[98:99]
	s_add_i32 m0, s100, 0x1800
	s_nop 0
	global_load_lds_dwordx4 v[244:245], off
	v_lshl_add_u64 v[244:245], v[244:245], 0, 64
	s_add_i32 m0, s100, 0x1c00
	s_nop 0
	global_load_lds_dwordx4 v[244:245], off
	v_add_u32_e32 v244, 0xa0, v158
	v_ashrrev_i32_e32 v245, 31, v244
	v_lshlrev_b64 v[244:245], 10, v[244:245]
	v_lshl_add_u64 v[244:245], v[244:245], 0, v[154:155]
	v_lshlrev_b64 v[244:245], 2, v[244:245]
	v_lshl_add_u64 v[244:245], s[90:91], 0, v[244:245]
	s_add_i32 m0, s100, 0x2000
	s_nop 0
	global_load_lds_dwordx4 v[244:245], off
	v_lshl_add_u64 v[244:245], v[244:245], 0, 64
	s_add_i32 m0, s100, 0x2400
	s_nop 0
	global_load_lds_dwordx4 v[244:245], off
	v_lshl_add_u64 v[244:245], v[244:245], 0, s[98:99]
	s_add_i32 m0, s100, 0x2800
	s_nop 0
	global_load_lds_dwordx4 v[244:245], off
	v_lshl_add_u64 v[244:245], v[244:245], 0, 64
	s_add_i32 m0, s100, 0x2c00
	s_nop 0
	global_load_lds_dwordx4 v[244:245], off
	v_add_u32_e32 v244, 0xb0, v158
	v_ashrrev_i32_e32 v245, 31, v244
	v_lshlrev_b64 v[244:245], 10, v[244:245]
	v_lshl_add_u64 v[244:245], v[244:245], 0, v[154:155]
	v_lshlrev_b64 v[244:245], 2, v[244:245]
	v_lshl_add_u64 v[244:245], s[90:91], 0, v[244:245]
	s_add_i32 m0, s100, 0x3000
	s_nop 0
	global_load_lds_dwordx4 v[244:245], off
	v_lshl_add_u64 v[244:245], v[244:245], 0, 64
	s_add_i32 m0, s100, 0x3400
	s_nop 0
	global_load_lds_dwordx4 v[244:245], off
	v_lshl_add_u64 v[244:245], v[244:245], 0, s[98:99]
	s_add_i32 m0, s100, 0x3800
	s_nop 0
	global_load_lds_dwordx4 v[244:245], off
	v_lshl_add_u64 v[244:245], v[244:245], 0, 64
	s_add_i32 m0, s100, 0x3c00
	s_nop 0
	global_load_lds_dwordx4 v[244:245], off
	global_load_dwordx4 v[172:175], v[162:163], off
	global_load_dwordx4 v[180:183], v[164:165], off
	global_load_dwordx4 v[140:143], v[162:163], off offset:64
	global_load_dwordx4 v[184:187], v[164:165], off offset:64
	global_load_dwordx4 v[136:139], v[162:163], off offset:512
	global_load_dwordx4 v[244:247], v[164:165], off offset:512
	global_load_dwordx4 v[132:135], v[162:163], off offset:576
	global_load_dwordx4 v[166:169], v[164:165], off offset:576
	s_cmp_eq_u64 s[30:31], 0
	s_waitcnt lgkmcnt(0)
	s_barrier
;     __device__ __forceinline__ void fused(f32x4 (&acc)[2][2][4][2], const Unit& u, int wr, int wc, int fr, int fq, LAS unsigned char* lds, int wid, int lane) const {
;     ...
;                 for (int n = 0; n < 2; ++n) cw[bj][n] = *(const f32x4*)(gate + mb + col0 + bj * HALF + n * 16) * *(const f32x4*)(gpost + col0 + bj * HALF + n * 16);
; #pragma unroll
;             for (int ai = 0; ai < 2; ++ai)
; #pragma unroll
;                 for (int m = 0; m < 4; ++m) { const int r = ai * HALF + wr * 64 + m * 16 + fr; const float r1 = rsqrtf(S[r] * (1.0f / D) + EPS) * wgt; const size_t off = (size_t)(u.pm * BM + r) * D + col0;
; #pragma unroll
;                     for (int bj = 0; bj < 2; ++bj)
; #pragma unroll
;                         for (int n = 0; n < 2; ++n) { const f32x4 xv = *(const f32x4*)(xin + off + bj * HALF + n * 16); const f32x4 xn = xv + (cw[bj][n] * r1) * acc[ai][bj][m][n];
;                             acc[ai][bj][m][n] = xn; *(f32x4*)(xout + off + bj * HALF + n * 16) = xn; }
;                     asm volatile("" : "+v"(acc[ai][0][m][0]), "+v"(acc[ai][0][m][1]), "+v"(acc[ai][1][m][0]), "+v"(acc[ai][1][m][1]));
;                     asm volatile("" ::: "memory"); }
	s_waitcnt vmcnt(0)
	v_pk_mul_f32 v[172:173], v[172:173], v[180:181]
	v_pk_mul_f32 v[174:175], v[174:175], v[182:183]
	v_pk_mul_f32 v[140:141], v[140:141], v[184:185]
	v_pk_mul_f32 v[142:143], v[142:143], v[186:187]
	v_pk_mul_f32 v[136:137], v[136:137], v[244:245]
	v_pk_mul_f32 v[138:139], v[138:139], v[246:247]
	v_pk_mul_f32 v[132:133], v[132:133], v[166:167]
	v_pk_mul_f32 v[134:135], v[134:135], v[168:169]
	ds_read_b32 v144, v208 offset:4096
	s_waitcnt lgkmcnt(0)
	v_fmamk_f32 v144, v144, 0x3a800000, v146
	v_cmp_gt_f32_e32 vcc, s67, v144
	v_mul_f32_e32 v244, 0x4b800000, v144
	s_nop 0
	v_cndmask_b32_e32 v144, v144, v244, vcc
	v_rsq_f32_e32 v144, v144
	s_nop 0
	v_mul_f32_e32 v244, 0x45800000, v144
	v_cndmask_b32_e32 v144, v144, v244, vcc
	v_mul_f32_e32 v144, v149, v144
	v_pk_mul_f32 v[184:185], v[172:173], v[144:145] op_sel_hi:[1,0]
	v_pk_mul_f32 v[186:187], v[174:175], v[144:145] op_sel_hi:[1,0]
	v_pk_fma_f32 v[88:89], v[88:89], v[184:185], v[212:213]
	v_pk_fma_f32 v[90:91], v[90:91], v[186:187], v[214:215]
	v_pk_mul_f32 v[184:185], v[140:141], v[144:145] op_sel_hi:[1,0]
	v_pk_mul_f32 v[186:187], v[142:143], v[144:145] op_sel_hi:[1,0]
	v_pk_fma_f32 v[104:105], v[104:105], v[184:185], v[216:217]
	v_pk_fma_f32 v[106:107], v[106:107], v[186:187], v[218:219]
	v_pk_mul_f32 v[184:185], v[136:137], v[144:145] op_sel_hi:[1,0]
	v_pk_mul_f32 v[186:187], v[138:139], v[144:145] op_sel_hi:[1,0]
	v_pk_fma_f32 v[100:101], v[100:101], v[184:185], v[220:221]
	v_pk_fma_f32 v[102:103], v[102:103], v[186:187], v[222:223]
	v_pk_mul_f32 v[184:185], v[132:133], v[144:145] op_sel_hi:[1,0]
	v_pk_mul_f32 v[186:187], v[134:135], v[144:145] op_sel_hi:[1,0]
	v_pk_fma_f32 v[84:85], v[84:85], v[184:185], v[224:225]
	v_pk_fma_f32 v[86:87], v[86:87], v[186:187], v[226:227]
	v_add_u32_e32 v160, 32, v158
	v_ashrrev_i32_e32 v161, 31, v160
	v_lshlrev_b64 v[246:247], 10, v[160:161]
	v_lshl_add_u64 v[246:247], v[246:247], 0, v[154:155]
	v_lshlrev_b64 v[246:247], 2, v[246:247]
	v_lshl_add_u64 v[246:247], s[90:91], 0, v[246:247]
	global_load_dwordx4 v[212:215], v[246:247], off
	global_load_dwordx4 v[216:219], v[246:247], off offset:64
	global_load_dwordx4 v[220:223], v[246:247], off offset:512
	global_load_dwordx4 v[224:227], v[246:247], off offset:576
	ds_read_b32 v144, v208 offset:4160
	s_waitcnt lgkmcnt(0)
	v_fmamk_f32 v144, v144, 0x3a800000, v146
	v_cmp_gt_f32_e32 vcc, s67, v144
	v_mul_f32_e32 v244, 0x4b800000, v144
	s_nop 0
	v_cndmask_b32_e32 v144, v144, v244, vcc
	v_rsq_f32_e32 v144, v144
	s_nop 0
	v_mul_f32_e32 v244, 0x45800000, v144
	v_cndmask_b32_e32 v144, v144, v244, vcc
	v_mul_f32_e32 v144, v149, v144
	v_pk_mul_f32 v[184:185], v[172:173], v[144:145] op_sel_hi:[1,0]
	v_pk_mul_f32 v[186:187], v[174:175], v[144:145] op_sel_hi:[1,0]
	v_pk_fma_f32 v[76:77], v[76:77], v[184:185], v[228:229]
	v_pk_fma_f32 v[78:79], v[78:79], v[186:187], v[230:231]
	v_pk_mul_f32 v[184:185], v[140:141], v[144:145] op_sel_hi:[1,0]
	v_pk_mul_f32 v[186:187], v[142:143], v[144:145] op_sel_hi:[1,0]
	v_pk_fma_f32 v[92:93], v[92:93], v[184:185], v[232:233]
	v_pk_fma_f32 v[94:95], v[94:95], v[186:187], v[234:235]
	v_pk_mul_f32 v[184:185], v[136:137], v[144:145] op_sel_hi:[1,0]
	v_pk_mul_f32 v[186:187], v[138:139], v[144:145] op_sel_hi:[1,0]
	v_pk_fma_f32 v[80:81], v[80:81], v[184:185], v[236:237]
	v_pk_fma_f32 v[82:83], v[82:83], v[186:187], v[238:239]
	v_pk_mul_f32 v[184:185], v[132:133], v[144:145] op_sel_hi:[1,0]
	v_pk_mul_f32 v[186:187], v[134:135], v[144:145] op_sel_hi:[1,0]
	v_pk_fma_f32 v[72:73], v[72:73], v[184:185], v[240:241]
	v_pk_fma_f32 v[74:75], v[74:75], v[186:187], v[242:243]
	v_add_u32_e32 v162, 48, v158
	v_ashrrev_i32_e32 v163, 31, v162
	v_lshlrev_b64 v[246:247], 10, v[162:163]
	v_lshl_add_u64 v[246:247], v[246:247], 0, v[154:155]
	v_lshlrev_b64 v[246:247], 2, v[246:247]
	v_lshl_add_u64 v[246:247], s[90:91], 0, v[246:247]
	global_load_dwordx4 v[228:231], v[246:247], off
	global_load_dwordx4 v[232:235], v[246:247], off offset:64
	global_load_dwordx4 v[236:239], v[246:247], off offset:512
	global_load_dwordx4 v[240:243], v[246:247], off offset:576
	ds_read_b32 v144, v208 offset:4224
	s_waitcnt lgkmcnt(0)
	v_fmamk_f32 v144, v144, 0x3a800000, v146
	v_cmp_gt_f32_e32 vcc, s67, v144
	v_mul_f32_e32 v244, 0x4b800000, v144
	s_nop 0
	v_cndmask_b32_e32 v144, v144, v244, vcc
	v_rsq_f32_e32 v144, v144
	s_nop 0
	v_mul_f32_e32 v244, 0x45800000, v144
	v_cndmask_b32_e32 v144, v144, v244, vcc
	v_mul_f32_e32 v144, v149, v144
	s_waitcnt vmcnt(4)
	v_pk_mul_f32 v[184:185], v[172:173], v[144:145] op_sel_hi:[1,0]
	v_pk_mul_f32 v[186:187], v[174:175], v[144:145] op_sel_hi:[1,0]
	v_pk_fma_f32 v[108:109], v[108:109], v[184:185], v[212:213]
	v_pk_fma_f32 v[110:111], v[110:111], v[186:187], v[214:215]
	v_pk_mul_f32 v[184:185], v[140:141], v[144:145] op_sel_hi:[1,0]
	v_pk_mul_f32 v[186:187], v[142:143], v[144:145] op_sel_hi:[1,0]
	v_pk_fma_f32 v[124:125], v[124:125], v[184:185], v[216:217]
	v_pk_fma_f32 v[126:127], v[126:127], v[186:187], v[218:219]
	v_pk_mul_f32 v[184:185], v[136:137], v[144:145] op_sel_hi:[1,0]
	v_pk_mul_f32 v[186:187], v[138:139], v[144:145] op_sel_hi:[1,0]
	v_pk_fma_f32 v[120:121], v[120:121], v[184:185], v[220:221]
	v_pk_fma_f32 v[122:123], v[122:123], v[186:187], v[222:223]
	v_pk_mul_f32 v[184:185], v[132:133], v[144:145] op_sel_hi:[1,0]
	v_pk_mul_f32 v[186:187], v[134:135], v[144:145] op_sel_hi:[1,0]
	v_pk_fma_f32 v[116:117], v[116:117], v[184:185], v[224:225]
	v_pk_fma_f32 v[118:119], v[118:119], v[186:187], v[226:227]
	ds_read_b32 v144, v208 offset:4288
	s_waitcnt lgkmcnt(0)
;     __device__ __forceinline__ void fused(f32x4 (&acc)[2][2][4][2], const Unit& u, int wr, int wc, int fr, int fq, LAS unsigned char* lds, int wid, int lane) const {
;     ...
;                 for (int m = 0; m < 4; ++m) { const int r = ai * HALF + wr * 64 + m * 16 + fr; const float r1 = rsqrtf(S[r] * (1.0f / D) + EPS) * wgt; const size_t off = (size_t)(u.pm * BM + r) * D + col0;
; #pragma unroll
;                     for (int bj = 0; bj < 2; ++bj)
; #pragma unroll
;                         for (int n = 0; n < 2; ++n) { const f32x4 xv = *(const f32x4*)(xin + off + bj * HALF + n * 16); const f32x4 xn = xv + (cw[bj][n] * r1) * acc[ai][bj][m][n];
;                             acc[ai][bj][m][n] = xn; *(f32x4*)(xout + off + bj * HALF + n * 16) = xn; }
;                     asm volatile("" : "+v"(acc[ai][0][m][0]), "+v"(acc[ai][0][m][1]), "+v"(acc[ai][1][m][0]), "+v"(acc[ai][1][m][1]));
;                     asm volatile("" ::: "memory"); }
	v_fmamk_f32 v144, v144, 0x3a800000, v146
	v_cmp_gt_f32_e32 vcc, s67, v144
	v_mul_f32_e32 v244, 0x4b800000, v144
	s_nop 0
	v_cndmask_b32_e32 v144, v144, v244, vcc
	v_rsq_f32_e32 v144, v144
	s_nop 0
	v_mul_f32_e32 v244, 0x45800000, v144
	v_cndmask_b32_e32 v144, v144, v244, vcc
	v_mul_f32_e32 v144, v149, v144
	s_waitcnt vmcnt(0)
	v_pk_mul_f32 v[184:185], v[172:173], v[144:145] op_sel_hi:[1,0]
	v_pk_mul_f32 v[186:187], v[174:175], v[144:145] op_sel_hi:[1,0]
	v_pk_fma_f32 v[112:113], v[112:113], v[184:185], v[228:229]
	v_pk_fma_f32 v[114:115], v[114:115], v[186:187], v[230:231]
	v_pk_mul_f32 v[184:185], v[140:141], v[144:145] op_sel_hi:[1,0]
	v_pk_mul_f32 v[186:187], v[142:143], v[144:145] op_sel_hi:[1,0]
	v_pk_fma_f32 v[96:97], v[96:97], v[184:185], v[232:233]
	v_pk_fma_f32 v[98:99], v[98:99], v[186:187], v[234:235]
	v_pk_mul_f32 v[184:185], v[136:137], v[144:145] op_sel_hi:[1,0]
	v_pk_mul_f32 v[186:187], v[138:139], v[144:145] op_sel_hi:[1,0]
	v_pk_fma_f32 v[68:69], v[68:69], v[184:185], v[236:237]
	v_pk_fma_f32 v[70:71], v[70:71], v[186:187], v[238:239]
	v_pk_mul_f32 v[184:185], v[132:133], v[144:145] op_sel_hi:[1,0]
	v_pk_mul_f32 v[186:187], v[134:135], v[144:145] op_sel_hi:[1,0]
	v_pk_fma_f32 v[64:65], v[64:65], v[184:185], v[240:241]
	v_pk_fma_f32 v[66:67], v[66:67], v[186:187], v[242:243]
	v_and_b32_e32 v212, 63, v147
	v_lshlrev_b32_e32 v212, 4, v212
	v_add_u32_e32 v212, s100, v212
	v_add_u32_e32 v164, 0x80, v158
	v_ashrrev_i32_e32 v165, 31, v164
	ds_read_b32 v144, v208 offset:4608
	s_waitcnt lgkmcnt(0)
	v_fmamk_f32 v144, v144, 0x3a800000, v146
	v_cmp_gt_f32_e32 vcc, s67, v144
	v_mul_f32_e32 v244, 0x4b800000, v144
	s_nop 0
	v_cndmask_b32_e32 v144, v144, v244, vcc
	v_rsq_f32_e32 v144, v144
	s_nop 0
	v_mul_f32_e32 v244, 0x45800000, v144
	v_cndmask_b32_e32 v144, v144, v244, vcc
	v_mul_f32_e32 v144, v149, v144
	ds_read_b128 v[216:219], v212 offset:0
	ds_read_b128 v[220:223], v212 offset:1024
	s_waitcnt lgkmcnt(1)
	v_pk_mul_f32 v[184:185], v[172:173], v[144:145] op_sel_hi:[1,0]
	v_pk_mul_f32 v[186:187], v[174:175], v[144:145] op_sel_hi:[1,0]
	v_pk_fma_f32 v[60:61], v[60:61], v[184:185], v[216:217]
	v_pk_fma_f32 v[62:63], v[62:63], v[186:187], v[218:219]
	ds_read_b128 v[216:219], v212 offset:2048
	s_waitcnt lgkmcnt(1)
	v_pk_mul_f32 v[184:185], v[140:141], v[144:145] op_sel_hi:[1,0]
	v_pk_mul_f32 v[186:187], v[142:143], v[144:145] op_sel_hi:[1,0]
	v_pk_fma_f32 v[56:57], v[56:57], v[184:185], v[220:221]
	v_pk_fma_f32 v[58:59], v[58:59], v[186:187], v[222:223]
	ds_read_b128 v[220:223], v212 offset:3072
	s_waitcnt lgkmcnt(1)
	v_pk_mul_f32 v[184:185], v[136:137], v[144:145] op_sel_hi:[1,0]
	v_pk_mul_f32 v[186:187], v[138:139], v[144:145] op_sel_hi:[1,0]
	v_pk_fma_f32 v[52:53], v[52:53], v[184:185], v[216:217]
	v_pk_fma_f32 v[54:55], v[54:55], v[186:187], v[218:219]
	s_waitcnt lgkmcnt(0)
	v_pk_mul_f32 v[184:185], v[132:133], v[144:145] op_sel_hi:[1,0]
	v_pk_mul_f32 v[186:187], v[134:135], v[144:145] op_sel_hi:[1,0]
	v_pk_fma_f32 v[48:49], v[48:49], v[184:185], v[220:221]
	v_pk_fma_f32 v[50:51], v[50:51], v[186:187], v[222:223]
	v_add_u32_e32 v166, 0x90, v158
	v_ashrrev_i32_e32 v167, 31, v166
	ds_read_b32 v144, v208 offset:4672
	s_waitcnt lgkmcnt(0)
	v_fmamk_f32 v144, v144, 0x3a800000, v146
	v_cmp_gt_f32_e32 vcc, s67, v144
	v_mul_f32_e32 v244, 0x4b800000, v144
	s_nop 0
	v_cndmask_b32_e32 v144, v144, v244, vcc
	v_rsq_f32_e32 v144, v144
	s_nop 0
	v_mul_f32_e32 v244, 0x45800000, v144
	v_cndmask_b32_e32 v144, v144, v244, vcc
	v_mul_f32_e32 v144, v149, v144
	ds_read_b128 v[216:219], v212 offset:4096
	ds_read_b128 v[220:223], v212 offset:5120
	s_waitcnt lgkmcnt(1)
	v_pk_mul_f32 v[184:185], v[172:173], v[144:145] op_sel_hi:[1,0]
	v_pk_mul_f32 v[186:187], v[174:175], v[144:145] op_sel_hi:[1,0]
	v_pk_fma_f32 v[44:45], v[44:45], v[184:185], v[216:217]
	v_pk_fma_f32 v[46:47], v[46:47], v[186:187], v[218:219]
	ds_read_b128 v[216:219], v212 offset:6144
	s_waitcnt lgkmcnt(1)
	v_pk_mul_f32 v[184:185], v[140:141], v[144:145] op_sel_hi:[1,0]
	v_pk_mul_f32 v[186:187], v[142:143], v[144:145] op_sel_hi:[1,0]
	v_pk_fma_f32 v[40:41], v[40:41], v[184:185], v[220:221]
	v_pk_fma_f32 v[42:43], v[42:43], v[186:187], v[222:223]
	ds_read_b128 v[220:223], v212 offset:7168
	s_waitcnt lgkmcnt(1)
	v_pk_mul_f32 v[184:185], v[136:137], v[144:145] op_sel_hi:[1,0]
	v_pk_mul_f32 v[186:187], v[138:139], v[144:145] op_sel_hi:[1,0]
	v_pk_fma_f32 v[36:37], v[36:37], v[184:185], v[216:217]
	v_pk_fma_f32 v[38:39], v[38:39], v[186:187], v[218:219]
	s_waitcnt lgkmcnt(0)
	v_pk_mul_f32 v[184:185], v[132:133], v[144:145] op_sel_hi:[1,0]
	v_pk_mul_f32 v[186:187], v[134:135], v[144:145] op_sel_hi:[1,0]
	v_pk_fma_f32 v[32:33], v[32:33], v[184:185], v[220:221]
	v_pk_fma_f32 v[34:35], v[34:35], v[186:187], v[222:223]
	v_add_u32_e32 v168, 0xa0, v158
	v_ashrrev_i32_e32 v169, 31, v168
	ds_read_b32 v144, v208 offset:4736
	s_waitcnt lgkmcnt(0)
	v_fmamk_f32 v144, v144, 0x3a800000, v146
	v_cmp_gt_f32_e32 vcc, s67, v144
	v_mul_f32_e32 v244, 0x4b800000, v144
	s_nop 0
	v_cndmask_b32_e32 v144, v144, v244, vcc
	v_rsq_f32_e32 v144, v144
	s_nop 0
	v_mul_f32_e32 v244, 0x45800000, v144
	v_cndmask_b32_e32 v144, v144, v244, vcc
	v_mul_f32_e32 v144, v149, v144
	ds_read_b128 v[216:219], v212 offset:8192
	ds_read_b128 v[220:223], v212 offset:9216
	s_waitcnt lgkmcnt(1)
	v_pk_mul_f32 v[184:185], v[172:173], v[144:145] op_sel_hi:[1,0]
	v_pk_mul_f32 v[186:187], v[174:175], v[144:145] op_sel_hi:[1,0]
	v_pk_fma_f32 v[28:29], v[28:29], v[184:185], v[216:217]
	v_pk_fma_f32 v[30:31], v[30:31], v[186:187], v[218:219]
	ds_read_b128 v[216:219], v212 offset:10240
	s_waitcnt lgkmcnt(1)
;     __device__ __forceinline__ void fused(f32x4 (&acc)[2][2][4][2], const Unit& u, int wr, int wc, int fr, int fq, LAS unsigned char* lds, int wid, int lane) const {
;     ...
;                 for (int m = 0; m < 4; ++m) { const int r = ai * HALF + wr * 64 + m * 16 + fr; const float r1 = rsqrtf(S[r] * (1.0f / D) + EPS) * wgt; const size_t off = (size_t)(u.pm * BM + r) * D + col0;
; #pragma unroll
;                     for (int bj = 0; bj < 2; ++bj)
; #pragma unroll
;                         for (int n = 0; n < 2; ++n) { const f32x4 xv = *(const f32x4*)(xin + off + bj * HALF + n * 16); const f32x4 xn = xv + (cw[bj][n] * r1) * acc[ai][bj][m][n];
;                             acc[ai][bj][m][n] = xn; *(f32x4*)(xout + off + bj * HALF + n * 16) = xn; }
;                     asm volatile("" : "+v"(acc[ai][0][m][0]), "+v"(acc[ai][0][m][1]), "+v"(acc[ai][1][m][0]), "+v"(acc[ai][1][m][1]));
;                     asm volatile("" ::: "memory"); }
;         }
;         if (H == nullptr) return;
	v_pk_mul_f32 v[184:185], v[140:141], v[144:145] op_sel_hi:[1,0]
	v_pk_mul_f32 v[186:187], v[142:143], v[144:145] op_sel_hi:[1,0]
	v_pk_fma_f32 v[24:25], v[24:25], v[184:185], v[220:221]
	v_pk_fma_f32 v[26:27], v[26:27], v[186:187], v[222:223]
	ds_read_b128 v[220:223], v212 offset:11264
	s_waitcnt lgkmcnt(1)
	v_pk_mul_f32 v[184:185], v[136:137], v[144:145] op_sel_hi:[1,0]
	v_pk_mul_f32 v[186:187], v[138:139], v[144:145] op_sel_hi:[1,0]
	v_pk_fma_f32 v[20:21], v[20:21], v[184:185], v[216:217]
	v_pk_fma_f32 v[22:23], v[22:23], v[186:187], v[218:219]
	s_waitcnt lgkmcnt(0)
	v_pk_mul_f32 v[184:185], v[132:133], v[144:145] op_sel_hi:[1,0]
	v_pk_mul_f32 v[186:187], v[134:135], v[144:145] op_sel_hi:[1,0]
	v_pk_fma_f32 v[16:17], v[16:17], v[184:185], v[220:221]
	v_pk_fma_f32 v[18:19], v[18:19], v[186:187], v[222:223]
	v_add_u32_e32 v170, 0xb0, v158
	v_ashrrev_i32_e32 v171, 31, v170
	ds_read_b32 v144, v208 offset:4800
	s_waitcnt lgkmcnt(0)
	v_fmamk_f32 v144, v144, 0x3a800000, v146
	v_cmp_gt_f32_e32 vcc, s67, v144
	v_mul_f32_e32 v244, 0x4b800000, v144
	s_nop 0
	v_cndmask_b32_e32 v144, v144, v244, vcc
	v_rsq_f32_e32 v144, v144
	s_nop 0
	v_mul_f32_e32 v244, 0x45800000, v144
	v_cndmask_b32_e32 v144, v144, v244, vcc
	v_mul_f32_e32 v144, v149, v144
	ds_read_b128 v[216:219], v212 offset:12288
	ds_read_b128 v[220:223], v212 offset:13312
	s_waitcnt lgkmcnt(1)
	v_pk_mul_f32 v[184:185], v[172:173], v[144:145] op_sel_hi:[1,0]
	v_pk_mul_f32 v[186:187], v[174:175], v[144:145] op_sel_hi:[1,0]
	v_pk_fma_f32 v[12:13], v[12:13], v[184:185], v[216:217]
	v_pk_fma_f32 v[14:15], v[14:15], v[186:187], v[218:219]
	ds_read_b128 v[216:219], v212 offset:14336
	s_waitcnt lgkmcnt(1)
	v_pk_mul_f32 v[184:185], v[140:141], v[144:145] op_sel_hi:[1,0]
	v_pk_mul_f32 v[186:187], v[142:143], v[144:145] op_sel_hi:[1,0]
	v_pk_fma_f32 v[8:9], v[8:9], v[184:185], v[220:221]
	v_pk_fma_f32 v[10:11], v[10:11], v[186:187], v[222:223]
	ds_read_b128 v[220:223], v212 offset:15360
	s_waitcnt lgkmcnt(1)
	v_pk_mul_f32 v[184:185], v[136:137], v[144:145] op_sel_hi:[1,0]
	v_pk_mul_f32 v[186:187], v[138:139], v[144:145] op_sel_hi:[1,0]
	v_pk_fma_f32 v[4:5], v[4:5], v[184:185], v[216:217]
	v_pk_fma_f32 v[6:7], v[6:7], v[186:187], v[218:219]
	s_waitcnt lgkmcnt(0)
	v_pk_mul_f32 v[184:185], v[132:133], v[144:145] op_sel_hi:[1,0]
	v_pk_mul_f32 v[186:187], v[134:135], v[144:145] op_sel_hi:[1,0]
	v_pk_fma_f32 v[0:1], v[0:1], v[184:185], v[220:221]
	v_pk_fma_f32 v[2:3], v[2:3], v[186:187], v[222:223]
	s_cbranch_scc0 .Lxs_skip
	v_lshlrev_b64 v[244:245], 10, v[158:159]
	v_lshl_add_u64 v[244:245], v[244:245], 0, v[154:155]
	v_lshlrev_b64 v[244:245], 2, v[244:245]
	v_lshl_add_u64 v[246:247], s[88:89], 0, v[244:245]
	global_store_dwordx4 v[246:247], v[88:91], off
	global_store_dwordx4 v[246:247], v[104:107], off offset:64
	global_store_dwordx4 v[246:247], v[100:103], off offset:512
	global_store_dwordx4 v[246:247], v[84:87], off offset:576
	v_lshlrev_b64 v[244:245], 10, v[156:157]
	v_lshl_add_u64 v[244:245], v[244:245], 0, v[154:155]
	v_lshlrev_b64 v[244:245], 2, v[244:245]
	v_lshl_add_u64 v[246:247], s[88:89], 0, v[244:245]
	global_store_dwordx4 v[246:247], v[76:79], off
	global_store_dwordx4 v[246:247], v[92:95], off offset:64
	global_store_dwordx4 v[246:247], v[80:83], off offset:512
	global_store_dwordx4 v[246:247], v[72:75], off offset:576
	v_lshlrev_b64 v[244:245], 10, v[160:161]
	v_lshl_add_u64 v[244:245], v[244:245], 0, v[154:155]
	v_lshlrev_b64 v[244:245], 2, v[244:245]
	v_lshl_add_u64 v[246:247], s[88:89], 0, v[244:245]
	global_store_dwordx4 v[246:247], v[108:111], off
	global_store_dwordx4 v[246:247], v[124:127], off offset:64
	global_store_dwordx4 v[246:247], v[120:123], off offset:512
	global_store_dwordx4 v[246:247], v[116:119], off offset:576
	v_lshlrev_b64 v[244:245], 10, v[162:163]
	v_lshl_add_u64 v[244:245], v[244:245], 0, v[154:155]
	v_lshlrev_b64 v[244:245], 2, v[244:245]
	v_lshl_add_u64 v[246:247], s[88:89], 0, v[244:245]
	global_store_dwordx4 v[246:247], v[112:115], off
	global_store_dwordx4 v[246:247], v[96:99], off offset:64
	global_store_dwordx4 v[246:247], v[68:71], off offset:512
	global_store_dwordx4 v[246:247], v[64:67], off offset:576
	v_lshlrev_b64 v[244:245], 10, v[164:165]
	v_lshl_add_u64 v[244:245], v[244:245], 0, v[154:155]
	v_lshlrev_b64 v[244:245], 2, v[244:245]
	v_lshl_add_u64 v[246:247], s[88:89], 0, v[244:245]
	global_store_dwordx4 v[246:247], v[60:63], off
	global_store_dwordx4 v[246:247], v[56:59], off offset:64
	global_store_dwordx4 v[246:247], v[52:55], off offset:512
	global_store_dwordx4 v[246:247], v[48:51], off offset:576
	v_lshlrev_b64 v[244:245], 10, v[166:167]
	v_lshl_add_u64 v[244:245], v[244:245], 0, v[154:155]
	v_lshlrev_b64 v[244:245], 2, v[244:245]
	v_lshl_add_u64 v[246:247], s[88:89], 0, v[244:245]
	global_store_dwordx4 v[246:247], v[44:47], off
	global_store_dwordx4 v[246:247], v[40:43], off offset:64
	global_store_dwordx4 v[246:247], v[36:39], off offset:512
	global_store_dwordx4 v[246:247], v[32:35], off offset:576
	v_lshlrev_b64 v[244:245], 10, v[168:169]
	v_lshl_add_u64 v[244:245], v[244:245], 0, v[154:155]
	v_lshlrev_b64 v[244:245], 2, v[244:245]
	v_lshl_add_u64 v[246:247], s[88:89], 0, v[244:245]
	global_store_dwordx4 v[246:247], v[28:31], off
	global_store_dwordx4 v[246:247], v[24:27], off offset:64
	global_store_dwordx4 v[246:247], v[20:23], off offset:512
	global_store_dwordx4 v[246:247], v[16:19], off offset:576
	v_lshlrev_b64 v[244:245], 10, v[170:171]
	v_lshl_add_u64 v[244:245], v[244:245], 0, v[154:155]
	v_lshlrev_b64 v[244:245], 2, v[244:245]
	v_lshl_add_u64 v[246:247], s[88:89], 0, v[244:245]
	global_store_dwordx4 v[246:247], v[12:15], off
	global_store_dwordx4 v[246:247], v[8:11], off offset:64
	global_store_dwordx4 v[246:247], v[4:7], off offset:512
	global_store_dwordx4 v[246:247], v[0:3], off offset:576

; #define LAS __attribute__((address_space(3)))
; __global__ void __launch_bounds__(512, 2) mega_fwd(KP kp) {
;     unsigned char* const smem = g_smem;
;     if (threadIdx.x < 29) *(LAS unsigned long long*)((LAS unsigned char*)g_smem + PTAB_OFF + 8 * threadIdx.x) = ((const unsigned long long*)__builtin_amdgcn_kernarg_segment_ptr())[threadIdx.x];
	.amdhsa_kernel _Z8mega_fwd2KP
		.amdhsa_group_segment_fixed_size 0
		.amdhsa_private_segment_fixed_size 0
		.amdhsa_kernarg_size 504
		.amdhsa_user_sgpr_count 2
		.amdhsa_user_sgpr_dispatch_ptr 0
		.amdhsa_user_sgpr_queue_ptr 0
		.amdhsa_user_sgpr_kernarg_segment_ptr 1
		.amdhsa_user_sgpr_dispatch_id 0
		.amdhsa_user_sgpr_kernarg_preload_length 0
		.amdhsa_user_sgpr_kernarg_preload_offset 0
		.amdhsa_user_sgpr_private_segment_size 0
		.amdhsa_uses_dynamic_stack 0
		.amdhsa_enable_private_segment 0
		.amdhsa_system_sgpr_workgroup_id_x 1
		.amdhsa_system_sgpr_workgroup_id_y 0
		.amdhsa_system_sgpr_workgroup_id_z 0
		.amdhsa_system_sgpr_workgroup_info 0
		.amdhsa_system_vgpr_workitem_id 2
		.amdhsa_next_free_vgpr 256
		.amdhsa_next_free_sgpr 102
		.amdhsa_accum_offset 256
		.amdhsa_reserve_vcc 1
		.amdhsa_float_round_mode_32 0
		.amdhsa_float_round_mode_16_64 0
		.amdhsa_float_denorm_mode_32 3
		.amdhsa_float_denorm_mode_16_64 3
		.amdhsa_dx10_clamp 1
		.amdhsa_ieee_mode 1
		.amdhsa_fp16_overflow 0
		.amdhsa_tg_split 0
		.amdhsa_exception_fp_ieee_invalid_op 0
		.amdhsa_exception_fp_denorm_src 0
		.amdhsa_exception_fp_ieee_div_zero 0
		.amdhsa_exception_fp_ieee_overflow 0
		.amdhsa_exception_fp_ieee_underflow 0
		.amdhsa_exception_fp_ieee_inexact 0
		.amdhsa_exception_int_div_zero 0
	.end_amdhsa_kernel

; #define LAS __attribute__((address_space(3)))
; __global__ void __launch_bounds__(512, 2) mega_fwd(KP kp) {
;     unsigned char* const smem = g_smem;
;     if (threadIdx.x < 29) *(LAS unsigned long long*)((LAS unsigned char*)g_smem + PTAB_OFF + 8 * threadIdx.x) = ((const unsigned long long*)__builtin_amdgcn_kernarg_segment_ptr())[threadIdx.x];
amdhsa.kernels:
  - .agpr_count:     0
    .args:
      - .offset:         0
        .size:           248
        .value_kind:     by_value
      - .offset:         248
        .size:           4
        .value_kind:     hidden_block_count_x
      - .offset:         252
        .size:           4
        .value_kind:     hidden_block_count_y
      - .offset:         256
        .size:           4
        .value_kind:     hidden_block_count_z
      - .offset:         260
        .size:           2
        .value_kind:     hidden_group_size_x
      - .offset:         262
        .size:           2
        .value_kind:     hidden_group_size_y
      - .offset:         264
        .size:           2
        .value_kind:     hidden_group_size_z
      - .offset:         266
        .size:           2
        .value_kind:     hidden_remainder_x
      - .offset:         268
        .size:           2
        .value_kind:     hidden_remainder_y
      - .offset:         270
        .size:           2
        .value_kind:     hidden_remainder_z
      - .offset:         288
        .size:           8
        .value_kind:     hidden_global_offset_x
      - .offset:         296
        .size:           8
        .value_kind:     hidden_global_offset_y
      - .offset:         304
        .size:           8
        .value_kind:     hidden_global_offset_z
      - .offset:         312
        .size:           2
        .value_kind:     hidden_grid_dims
      - .offset:         336
        .size:           8
        .value_kind:     hidden_multigrid_sync_arg
      - .offset:         368
        .size:           4
        .value_kind:     hidden_dynamic_lds_size
    .group_segment_fixed_size: 0
    .kernarg_segment_align: 8
    .kernarg_segment_size: 504
    .language:       OpenCL C
    .language_version:
      - 2
      - 0
    .max_flat_workgroup_size: 512
    .name:           _Z8mega_fwd2KP
    .private_segment_fixed_size: 0
    .sgpr_count:     108
    .sgpr_spill_count: 295
    .symbol:         _Z8mega_fwd2KP.kd
    .uniform_work_group_size: 1
    .uses_dynamic_stack: false
    .vgpr_count:     256
    .vgpr_spill_count: 0
    .wavefront_size: 64
